# GLA scan: packed-state rows 16-31 shifted by 64 B in LDS so the output waves' state reads hit distinct banks; on top of the nt output stores
# baseline (speedup 1.0000x reference)
.LBB0_153:
	s_andn2_b64 vcc, exec, s[0:1]
	s_cbranch_vccnz .LBB0_176
	s_and_b32 s0, s2, 7
	s_lshr_b32 s1, s2, 3
	s_and_b32 s5, s1, 3
	s_lshl_b32 s0, s0, 2
	s_add_i32 s0, s0, s5
	s_lshr_b32 s1, s1, 2
	v_lshrrev_b32_e32 v92, 6, v220
	s_nop 0
	v_readfirstlane_b32 s5, v92
	s_nop 0
	s_and_b32 s7, s5, 3
	s_lshr_b32 s9, s5, 2
	s_movk_i32 s14, 0x110
	s_movk_i32 s15, 0x90
	s_movk_i32 s45, 0x1a00
	v_and_b32_e32 v92, 15, v227
	v_lshrrev_b32_e32 v93, 4, v227
	v_and_b32_e32 v94, 31, v227
	v_lshrrev_b32_e32 v95, 5, v227
	s_mov_b32 s50, 91136
	s_lshl_b32 s51, s7, 6
	s_add_i32 s51, s51, s50
	v_mul_u32_u24_e32 v164, s14, v94
	v_lshl_add_u32 v164, v95, 3, v164
	v_add_u32_e32 v164, s51, v164
	v_lshrrev_b32_e32 v208, 4, v94
	v_lshl_add_u32 v164, v208, 6, v164
	s_lshl_b32 s50, s7, 7
	s_add_i32 s50, s50, 35840
	v_lshlrev_b32_e32 v208, 4, v95
	v_add_u32_e32 v208, s50, v208
	s_mul_i32 s50, s7, 4608
	s_add_i32 s50, s50, 17408
	v_mul_u32_u24_e32 v209, s15, v94
	v_lshl_add_u32 v209, v95, 4, v209
	v_add_u32_e32 v209, s50, v209
	s_mov_b32 s50, 36352
	v_mul_u32_u24_e32 v210, s15, v94
	v_lshl_add_u32 v210, v95, 4, v210
	v_add_u32_e32 v210, s50, v210
	v_mov_b32_e32 v0, 0
	v_mov_b32_e32 v1, 0
	v_mov_b32_e32 v2, 0
	v_mov_b32_e32 v3, 0
	v_mov_b32_e32 v4, 0
	v_mov_b32_e32 v5, 0
	v_mov_b32_e32 v6, 0
	v_mov_b32_e32 v7, 0
	v_mov_b32_e32 v8, 0
	v_mov_b32_e32 v9, 0
	v_mov_b32_e32 v10, 0
	v_mov_b32_e32 v11, 0
	v_mov_b32_e32 v12, 0
	v_mov_b32_e32 v13, 0
	v_mov_b32_e32 v14, 0
	v_mov_b32_e32 v15, 0
	s_mov_b32 s44, 0
	s_cmp_eq_u32 s9, 0
	s_cbranch_scc1 .Lsc_osetup
	s_lshl_b32 s14, s0, 20
	s_add_u32 s24, s92, s14
	s_addc_u32 s25, s93, 0
	s_add_u32 s28, s24, 0x2000000
	s_addc_u32 s29, s25, 0
	s_add_u32 s24, s24, 0x1000
	s_addc_u32 s25, s25, 0
	s_add_u32 s46, s24, 0x2000
	s_addc_u32 s47, s25, 0
	s_add_u32 s28, s28, 0x1000
	s_addc_u32 s29, s29, 0
	s_add_u32 s48, s28, 0x2000
	s_addc_u32 s49, s29, 0
	s_lshl_b32 s14, s0, 15
	s_add_u32 s14, s14, 0x1fdbb400
	s_add_u32 s38, s20, s14
	s_addc_u32 s39, s21, 0
	s_lshl_b32 s14, s0, 21
	s_add_u32 s15, s14, 0x1cdc4000
	s_sub_u32 s14, s14, 0x3000000
	s_add_u32 s14, s14, 0x29c4000
	s_cmp_lt_u32 s0, 24
	s_cselect_b32 s14, s15, s14
	s_lshl_b32 s15, s1, 12
	s_add_u32 s14, s14, s15
	s_add_u32 s14, s14, 0x1000
	s_add_u32 s40, s20, s14
	s_addc_u32 s41, s21, 0
	s_movk_i32 s14, 0x110
	s_movk_i32 s15, 0x90
	v_and_b32_e32 v92, 0xff, v220
	v_lshlrev_b32_e32 v236, 4, v92
	v_and_b32_e32 v93, 31, v92
	v_lshlrev_b32_e32 v239, 4, v93
	v_add_u32_e32 v239, 35840, v239
	v_lshrrev_b32_e32 v93, 4, v92
	v_and_b32_e32 v94, 15, v92
	v_lshlrev_b32_e32 v94, 4, v94
	v_mad_u32_u24 v237, v93, s14, v94
	v_lshrrev_b32_e32 v93, 3, v92
	v_and_b32_e32 v94, 7, v92
	v_lshlrev_b32_e32 v94, 4, v94
	v_mad_u32_u24 v238, v93, s15, v94
	v_add_u32_e32 v166, 36352, v238
	v_add_u32_e32 v238, 17408, v238
	global_load_dwordx4 v[24:27], v236, s[24:25] offset:-4096
	global_load_dwordx4 v[28:31], v236, s[24:25]
	global_load_dwordx4 v[32:35], v236, s[46:47] offset:-4096
	global_load_dwordx4 v[36:39], v236, s[46:47]
	global_load_dwordx4 v[40:43], v236, s[28:29] offset:-4096
	global_load_dwordx4 v[44:47], v236, s[28:29]
	global_load_dwordx4 v[48:51], v236, s[48:49] offset:-4096
	global_load_dwordx4 v[52:55], v236, s[48:49]
	global_load_dwordx4 v[56:59], v236, s[40:41] offset:-4096
	global_load_dwordx4 v[60:63], v239, s[38:39]
	s_add_u32 s24, s24, 0x4000
	s_addc_u32 s25, s25, 0
	s_add_u32 s46, s46, 0x4000
	s_addc_u32 s47, s47, 0
	s_add_u32 s28, s28, 0x4000
	s_addc_u32 s29, s29, 0
	s_add_u32 s48, s48, 0x4000
	s_addc_u32 s49, s49, 0
	s_add_u32 s40, s40, 0x8000
	s_addc_u32 s41, s41, 0
	s_add_u32 s38, s38, 0x200
	s_addc_u32 s39, s39, 0
	global_load_dwordx4 v[64:67], v236, s[24:25] offset:-4096
	global_load_dwordx4 v[68:71], v236, s[24:25]
	global_load_dwordx4 v[72:75], v236, s[46:47] offset:-4096
	global_load_dwordx4 v[76:79], v236, s[46:47]
	global_load_dwordx4 v[80:83], v236, s[28:29] offset:-4096
	global_load_dwordx4 v[84:87], v236, s[28:29]
	global_load_dwordx4 v[88:91], v236, s[48:49] offset:-4096
	global_load_dwordx4 v[92:95], v236, s[48:49]
	global_load_dwordx4 v[144:147], v236, s[40:41] offset:-4096
	global_load_dwordx4 v[148:151], v239, s[38:39]
	s_add_u32 s24, s24, 0x4000
	s_addc_u32 s25, s25, 0
	s_add_u32 s46, s46, 0x4000
	s_addc_u32 s47, s47, 0
	s_add_u32 s28, s28, 0x4000
	s_addc_u32 s29, s29, 0
	s_add_u32 s48, s48, 0x4000
	s_addc_u32 s49, s49, 0
	s_add_u32 s40, s40, 0x8000
	s_addc_u32 s41, s41, 0
	s_add_u32 s38, s38, 0x200
	s_addc_u32 s39, s39, 0
	global_load_dwordx4 v[152:155], v236, s[24:25] offset:-4096
	global_load_dwordx4 v[156:159], v236, s[24:25]
	global_load_dwordx4 v[160:163], v236, s[46:47] offset:-4096
	global_load_dwordx4 v[172:175], v236, s[46:47]
	global_load_dwordx4 v[180:183], v236, s[28:29] offset:-4096
	global_load_dwordx4 v[184:187], v236, s[28:29]
	global_load_dwordx4 v[188:191], v236, s[48:49] offset:-4096
	global_load_dwordx4 v[192:195], v236, s[48:49]
	global_load_dwordx4 v[196:199], v236, s[40:41] offset:-4096
	global_load_dwordx4 v[200:203], v239, s[38:39]
	s_add_u32 s24, s24, 0x4000
	s_addc_u32 s25, s25, 0
	s_add_u32 s46, s46, 0x4000
	s_addc_u32 s47, s47, 0
	s_add_u32 s28, s28, 0x4000
	s_addc_u32 s29, s29, 0
	s_add_u32 s48, s48, 0x4000
	s_addc_u32 s49, s49, 0
	s_add_u32 s40, s40, 0x8000
	s_addc_u32 s41, s41, 0
	s_add_u32 s38, s38, 0x200
	s_addc_u32 s39, s39, 0
	s_waitcnt vmcnt(20)
	ds_write_b128 v237, v[24:27] offset:0
	ds_write_b128 v237, v[28:31] offset:4352
	ds_write_b128 v237, v[32:35] offset:8704
	ds_write_b128 v237, v[36:39] offset:13056
	ds_write_b128 v238, v[40:43] offset:0
	ds_write_b128 v238, v[44:47] offset:4608
	ds_write_b128 v238, v[48:51] offset:9216
	ds_write_b128 v238, v[52:55] offset:13824
	ds_write_b128 v166, v[56:59] offset:0
	ds_write_b128 v239, v[60:63] offset:0
	s_waitcnt lgkmcnt(0)
	s_barrier

.Lsc_osetup:
	s_lshr_b32 s14, s0, 2
	s_mul_i32 s14, s14, 0x1a00000
	s_add_u32 s42, s96, s14
	s_addc_u32 s43, s97, 0
	s_movk_i32 s14, 0x110
	s_lshl_b32 s50, s7, 4
	v_add_u32_e32 v88, s50, v92
	v_mul_u32_u24_e32 v88, s14, v88
	v_lshl_add_u32 v88, v93, 4, v88
	v_add_u32_e32 v90, s50, v92
	v_mul_u32_u24_e32 v90, s45, v90
	s_and_b32 s50, s0, 3
	s_lshl_b32 s50, s50, 9
	s_lshl_b32 s51, s1, 6
	s_add_i32 s50, s50, s51
	v_lshl_add_u32 v90, v93, 4, v90
	v_add_u32_e32 v90, s50, v90
	v_lshrrev_b32_e32 v94, 2, v92
	v_and_b32_e32 v95, 3, v92
	v_lshl_add_u32 v94, v94, 3, v95
	v_mul_u32_u24_e32 v89, s14, v94
	v_lshl_add_u32 v89, v93, 4, v89
	v_add_u32_e32 v89, 91136, v89
	v_lshrrev_b32_e32 v95, 4, v94
	v_lshl_add_u32 v89, v95, 6, v89
	s_barrier
